# GEMM1 plain bf16 epilogue: lane-transposed stores via ds_bpermute (64B contiguous per 4 adjacent lanes)
# speedup vs baseline: 1.0154x; 1.0154x over previous
;     DI void operator()(const f32x4 (&acc)[2][2][4][2], const pg8::Unit& u, int wr, int wc, int fr, int fq) const {
;     ...
;         const bool rope = (pn >= 16 && pn < 26 && wc == 0);
;         const int row0 = u.pm * 256 + wr * 64 + fr, col0 = colt + wc * 32 + 8 * fq;
;         if (rope) {
;     ...
;         } else if (pn >= 36) {
.LBB0_130:
	s_add_i32 s41, s50, -16
	s_cmp_gt_u32 s41, 9
	s_cselect_b64 s[56:57], -1, 0
	s_or_b64 s[56:57], s[38:39], s[56:57]
	s_mov_b64 s[54:55], -1
	v_lshl_add_u32 v198, s52, 8, v207
	v_add_u32_e32 v184, s18, v209
	s_and_b64 vcc, exec, s[56:57]
	s_cbranch_vccz .LBB0_136
	s_cmp_gt_i32 s50, 35
	s_mov_b64 s[52:53], -1
	s_cbranch_scc1 .LBB0_133
; DI unsigned cvtpk(float lo, float hi) { unsigned r; asm volatile("v_cvt_pk_bf16_f32 %0, %1, %2" : "=v"(r) : "v"(lo), "v"(hi)); return r; }
;     DI void operator()(const f32x4 (&acc)[2][2][4][2], const pg8::Unit& u, int wr, int wc, int fr, int fq) const {
;     ...
;         } else {
; #pragma unroll
;             for (int ai = 0; ai < 2; ++ai)
; #pragma unroll
;                 for (int m = 0; m < 4; ++m) {
;                     const int row = row0 + ai * 128 + m * 16;
; #pragma unroll
;                     for (int bj = 0; bj < 2; ++bj) {
;                         const f32x4 v0 = acc[ai][bj][m][0], v1 = acc[ai][bj][m][1];
;                         u32x4 w = {cvtpk(v0[0], v0[1]), cvtpk(v0[2], v0[3]), cvtpk(v1[0], v1[1]), cvtpk(v1[2], v1[3])};
;                         __builtin_nontemporal_store(w, (u32x4*)(base + (size_t)row * ld + col0 + bj * 128));
;                     }
;                 }
	v_and_b32_e32 v213, 15, v202
	v_bfe_u32 v214, v202, 2, 4
	v_bfe_u32 v215, v202, 4, 2
	v_and_b32_e32 v216, 3, v202
	v_sub_u32_e32 v217, v214, v213
	v_add_u32_e32 v217, v198, v217
	v_sub_u32_e32 v218, v216, v215
	v_lshl_add_u32 v234, v218, 3, v184
	v_mov_b32_e32 v235, 0
	v_lshl_or_b32 v220, v216, 4, v214
	v_lshlrev_b32_e32 v220, 2, v220
	v_lshl_add_u64 v[236:237], v[234:235], 1, s[6:7]
	v_mov_b32_e32 v239, 0
	v_mul_lo_u32 v238, v217, s48
	v_lshl_add_u64 v[224:225], v[238:239], 1, v[236:237]
	v_cvt_pk_bf16_f32 v143, v124, v125
	v_cvt_pk_bf16_f32 v144, v126, v127
	v_cvt_pk_bf16_f32 v145, v120, v121
	v_cvt_pk_bf16_f32 v146, v122, v123
	ds_bpermute_b32 v124, v220, v143
	ds_bpermute_b32 v125, v220, v144
	ds_bpermute_b32 v126, v220, v145
	ds_bpermute_b32 v127, v220, v146
	v_cvt_pk_bf16_f32 v147, v116, v117
	v_cvt_pk_bf16_f32 v148, v118, v119
	v_cvt_pk_bf16_f32 v149, v112, v113
	v_cvt_pk_bf16_f32 v150, v114, v115
	ds_bpermute_b32 v116, v220, v147
	ds_bpermute_b32 v117, v220, v148
	ds_bpermute_b32 v118, v220, v149
	ds_bpermute_b32 v119, v220, v150
	s_waitcnt lgkmcnt(4)
	global_store_dwordx4 v[224:225], v[124:127], off nt
	v_add_u32_e32 v238, 16, v217
	v_mul_lo_u32 v238, v238, s48
	v_lshl_add_u64 v[226:227], v[238:239], 1, v[236:237]
	v_cvt_pk_bf16_f32 v151, v108, v109
	v_cvt_pk_bf16_f32 v152, v110, v111
	v_cvt_pk_bf16_f32 v153, v104, v105
	v_cvt_pk_bf16_f32 v154, v106, v107
	ds_bpermute_b32 v108, v220, v151
	ds_bpermute_b32 v109, v220, v152
	ds_bpermute_b32 v110, v220, v153
	ds_bpermute_b32 v111, v220, v154
	s_waitcnt lgkmcnt(4)
	global_store_dwordx4 v[224:225], v[116:119], off offset:256 nt
	v_cvt_pk_bf16_f32 v155, v100, v101
	v_cvt_pk_bf16_f32 v156, v102, v103
	v_cvt_pk_bf16_f32 v157, v96, v97
	v_cvt_pk_bf16_f32 v158, v98, v99
	ds_bpermute_b32 v100, v220, v155
	ds_bpermute_b32 v101, v220, v156
	ds_bpermute_b32 v102, v220, v157
	ds_bpermute_b32 v103, v220, v158
	s_waitcnt lgkmcnt(4)
	global_store_dwordx4 v[226:227], v[108:111], off nt
	v_add_u32_e32 v238, 32, v217
	v_mul_lo_u32 v238, v238, s48
	v_lshl_add_u64 v[228:229], v[238:239], 1, v[236:237]
	v_cvt_pk_bf16_f32 v143, v92, v93
	v_cvt_pk_bf16_f32 v144, v94, v95
	v_cvt_pk_bf16_f32 v145, v88, v89
	v_cvt_pk_bf16_f32 v146, v90, v91
	ds_bpermute_b32 v92, v220, v143
	ds_bpermute_b32 v93, v220, v144
	ds_bpermute_b32 v94, v220, v145
	ds_bpermute_b32 v95, v220, v146
	s_waitcnt lgkmcnt(4)
	global_store_dwordx4 v[226:227], v[100:103], off offset:256 nt
	v_cvt_pk_bf16_f32 v147, v84, v85
	v_cvt_pk_bf16_f32 v148, v86, v87
	v_cvt_pk_bf16_f32 v149, v80, v81
	v_cvt_pk_bf16_f32 v150, v82, v83
	ds_bpermute_b32 v84, v220, v147
	ds_bpermute_b32 v85, v220, v148
	ds_bpermute_b32 v86, v220, v149
	ds_bpermute_b32 v87, v220, v150
	s_waitcnt lgkmcnt(4)
	global_store_dwordx4 v[228:229], v[92:95], off nt
	v_add_u32_e32 v238, 48, v217
	v_mul_lo_u32 v238, v238, s48
	v_lshl_add_u64 v[230:231], v[238:239], 1, v[236:237]
	v_cvt_pk_bf16_f32 v151, v76, v77
	v_cvt_pk_bf16_f32 v152, v78, v79
	v_cvt_pk_bf16_f32 v153, v72, v73
	v_cvt_pk_bf16_f32 v154, v74, v75
	ds_bpermute_b32 v76, v220, v151
	ds_bpermute_b32 v77, v220, v152
	ds_bpermute_b32 v78, v220, v153
	ds_bpermute_b32 v79, v220, v154
	s_waitcnt lgkmcnt(4)
	global_store_dwordx4 v[228:229], v[84:87], off offset:256 nt
	v_cvt_pk_bf16_f32 v155, v68, v69
	v_cvt_pk_bf16_f32 v156, v70, v71
	v_cvt_pk_bf16_f32 v157, v64, v65
	v_cvt_pk_bf16_f32 v158, v66, v67
	ds_bpermute_b32 v68, v220, v155
	ds_bpermute_b32 v69, v220, v156
	ds_bpermute_b32 v70, v220, v157
	ds_bpermute_b32 v71, v220, v158
	s_waitcnt lgkmcnt(4)
	global_store_dwordx4 v[230:231], v[76:79], off nt
	v_add_u32_e32 v238, 0x80, v217
	v_mul_lo_u32 v238, v238, s48
	v_lshl_add_u64 v[224:225], v[238:239], 1, v[236:237]
	v_cvt_pk_bf16_f32 v143, v60, v61
	v_cvt_pk_bf16_f32 v144, v62, v63
	v_cvt_pk_bf16_f32 v145, v56, v57
	v_cvt_pk_bf16_f32 v146, v58, v59
	ds_bpermute_b32 v60, v220, v143
	ds_bpermute_b32 v61, v220, v144
	ds_bpermute_b32 v62, v220, v145
	ds_bpermute_b32 v63, v220, v146
	s_waitcnt lgkmcnt(4)
	global_store_dwordx4 v[230:231], v[68:71], off offset:256 nt
	v_cvt_pk_bf16_f32 v147, v52, v53
	v_cvt_pk_bf16_f32 v148, v54, v55
	v_cvt_pk_bf16_f32 v149, v48, v49
	v_cvt_pk_bf16_f32 v150, v50, v51
	ds_bpermute_b32 v52, v220, v147
	ds_bpermute_b32 v53, v220, v148
	ds_bpermute_b32 v54, v220, v149
	ds_bpermute_b32 v55, v220, v150
	s_waitcnt lgkmcnt(4)
	global_store_dwordx4 v[224:225], v[60:63], off nt
	v_add_u32_e32 v238, 0x90, v217
	v_mul_lo_u32 v238, v238, s48
	v_lshl_add_u64 v[226:227], v[238:239], 1, v[236:237]
	v_cvt_pk_bf16_f32 v151, v44, v45
	v_cvt_pk_bf16_f32 v152, v46, v47
	v_cvt_pk_bf16_f32 v153, v40, v41
	v_cvt_pk_bf16_f32 v154, v42, v43
	ds_bpermute_b32 v44, v220, v151
	ds_bpermute_b32 v45, v220, v152
	ds_bpermute_b32 v46, v220, v153
	ds_bpermute_b32 v47, v220, v154
	s_waitcnt lgkmcnt(4)
	global_store_dwordx4 v[224:225], v[52:55], off offset:256 nt
	v_cvt_pk_bf16_f32 v155, v36, v37
	v_cvt_pk_bf16_f32 v156, v38, v39
	v_cvt_pk_bf16_f32 v157, v32, v33
	v_cvt_pk_bf16_f32 v158, v34, v35
	ds_bpermute_b32 v36, v220, v155
	ds_bpermute_b32 v37, v220, v156
	ds_bpermute_b32 v38, v220, v157
	ds_bpermute_b32 v39, v220, v158
	s_waitcnt lgkmcnt(4)
	global_store_dwordx4 v[226:227], v[44:47], off nt
	v_add_u32_e32 v238, 0xa0, v217
	v_mul_lo_u32 v238, v238, s48
	v_lshl_add_u64 v[228:229], v[238:239], 1, v[236:237]
	v_cvt_pk_bf16_f32 v143, v28, v29
	v_cvt_pk_bf16_f32 v144, v30, v31
	v_cvt_pk_bf16_f32 v145, v24, v25
	v_cvt_pk_bf16_f32 v146, v26, v27
	ds_bpermute_b32 v28, v220, v143
	ds_bpermute_b32 v29, v220, v144
	ds_bpermute_b32 v30, v220, v145
	ds_bpermute_b32 v31, v220, v146
	s_waitcnt lgkmcnt(4)
	global_store_dwordx4 v[226:227], v[36:39], off offset:256 nt
	v_cvt_pk_bf16_f32 v147, v20, v21
	v_cvt_pk_bf16_f32 v148, v22, v23
	v_cvt_pk_bf16_f32 v149, v16, v17
	v_cvt_pk_bf16_f32 v150, v18, v19
	ds_bpermute_b32 v20, v220, v147
	ds_bpermute_b32 v21, v220, v148
	ds_bpermute_b32 v22, v220, v149
	ds_bpermute_b32 v23, v220, v150
	s_waitcnt lgkmcnt(4)
	global_store_dwordx4 v[228:229], v[28:31], off nt
	v_add_u32_e32 v238, 0xb0, v217
	v_mul_lo_u32 v238, v238, s48
	v_lshl_add_u64 v[230:231], v[238:239], 1, v[236:237]
	v_cvt_pk_bf16_f32 v151, v12, v13
	v_cvt_pk_bf16_f32 v152, v14, v15
	v_cvt_pk_bf16_f32 v153, v8, v9
	v_cvt_pk_bf16_f32 v154, v10, v11
	ds_bpermute_b32 v12, v220, v151
	ds_bpermute_b32 v13, v220, v152
	ds_bpermute_b32 v14, v220, v153
	ds_bpermute_b32 v15, v220, v154
	s_waitcnt lgkmcnt(4)
	global_store_dwordx4 v[228:229], v[20:23], off offset:256 nt
	v_cvt_pk_bf16_f32 v155, v4, v5
	v_cvt_pk_bf16_f32 v156, v6, v7
	v_cvt_pk_bf16_f32 v157, v0, v1
	v_cvt_pk_bf16_f32 v158, v2, v3
	ds_bpermute_b32 v4, v220, v155
	ds_bpermute_b32 v5, v220, v156
	ds_bpermute_b32 v6, v220, v157
	ds_bpermute_b32 v7, v220, v158
	s_waitcnt lgkmcnt(4)
	global_store_dwordx4 v[230:231], v[12:15], off nt
	s_waitcnt lgkmcnt(0)
	global_store_dwordx4 v[230:231], v[4:7], off offset:256 nt
	s_mov_b64 s[52:53], 0

; __global__ void __launch_bounds__(512, 2) mega(Params p) {
	.amdhsa_kernel _Z4mega6Params
		.amdhsa_group_segment_fixed_size 0
		.amdhsa_private_segment_fixed_size 0
		.amdhsa_kernarg_size 472
		.amdhsa_user_sgpr_count 2
		.amdhsa_user_sgpr_dispatch_ptr 0
		.amdhsa_user_sgpr_queue_ptr 0
		.amdhsa_user_sgpr_kernarg_segment_ptr 1
		.amdhsa_user_sgpr_dispatch_id 0
		.amdhsa_user_sgpr_kernarg_preload_length 0
		.amdhsa_user_sgpr_kernarg_preload_offset 0
		.amdhsa_user_sgpr_private_segment_size 0
		.amdhsa_uses_dynamic_stack 0
		.amdhsa_enable_private_segment 0
		.amdhsa_system_sgpr_workgroup_id_x 1
		.amdhsa_system_sgpr_workgroup_id_y 0
		.amdhsa_system_sgpr_workgroup_id_z 0
		.amdhsa_system_sgpr_workgroup_info 0
		.amdhsa_system_vgpr_workitem_id 2
		.amdhsa_next_free_vgpr 256
		.amdhsa_next_free_sgpr 98
		.amdhsa_accum_offset 256
		.amdhsa_reserve_vcc 1
		.amdhsa_float_round_mode_32 0
		.amdhsa_float_round_mode_16_64 0
		.amdhsa_float_denorm_mode_32 3
		.amdhsa_float_denorm_mode_16_64 3
		.amdhsa_dx10_clamp 1
		.amdhsa_ieee_mode 1
		.amdhsa_fp16_overflow 0
		.amdhsa_tg_split 0
		.amdhsa_exception_fp_ieee_invalid_op 0
		.amdhsa_exception_fp_denorm_src 0
		.amdhsa_exception_fp_ieee_div_zero 0
		.amdhsa_exception_fp_ieee_overflow 0
		.amdhsa_exception_fp_ieee_underflow 0
		.amdhsa_exception_fp_ieee_inexact 0
		.amdhsa_exception_int_div_zero 0
	.end_amdhsa_kernel

; __global__ void __launch_bounds__(512, 2) mega(Params p) {
amdhsa.kernels:
  - .agpr_count:     0
    .args:
      - .offset:         0
        .size:           216
        .value_kind:     by_value
      - .offset:         216
        .size:           4
        .value_kind:     hidden_block_count_x
      - .offset:         220
        .size:           4
        .value_kind:     hidden_block_count_y
      - .offset:         224
        .size:           4
        .value_kind:     hidden_block_count_z
      - .offset:         228
        .size:           2
        .value_kind:     hidden_group_size_x
      - .offset:         230
        .size:           2
        .value_kind:     hidden_group_size_y
      - .offset:         232
        .size:           2
        .value_kind:     hidden_group_size_z
      - .offset:         234
        .size:           2
        .value_kind:     hidden_remainder_x
      - .offset:         236
        .size:           2
        .value_kind:     hidden_remainder_y
      - .offset:         238
        .size:           2
        .value_kind:     hidden_remainder_z
      - .offset:         256
        .size:           8
        .value_kind:     hidden_global_offset_x
      - .offset:         264
        .size:           8
        .value_kind:     hidden_global_offset_y
      - .offset:         272
        .size:           8
        .value_kind:     hidden_global_offset_z
      - .offset:         280
        .size:           2
        .value_kind:     hidden_grid_dims
      - .offset:         304
        .size:           8
        .value_kind:     hidden_multigrid_sync_arg
      - .offset:         336
        .size:           4
        .value_kind:     hidden_dynamic_lds_size
    .group_segment_fixed_size: 0
    .kernarg_segment_align: 8
    .kernarg_segment_size: 472
    .language:       OpenCL C
    .language_version:
      - 2
      - 0
    .max_flat_workgroup_size: 512
    .name:           _Z4mega6Params
    .private_segment_fixed_size: 0
    .sgpr_count:     104
    .sgpr_spill_count: 0
    .symbol:         _Z4mega6Params.kd
    .uniform_work_group_size: 1
    .uses_dynamic_stack: false
    .vgpr_count:     256
    .vgpr_spill_count: 0
    .wavefront_size: 64
